# gather: issue batch-B u rows at loop top into spare VGPRs, counted vmcnt instead of 4 vmcnt(0) drains per iteration
# speedup vs baseline: 1.0836x; 1.0266x over previous
; __device__ void peer_gather_phase(const Params& P, int l, bool do_store) {
;     ...
;     auto load_batch = [&](uint2 (&u6)[12], uint2 (&v8)[8], int bt) {
;       const int evs = (bt < 8) ? ev0 : ev1;
;       const int kb = (bt & 7) * 8;
; #pragma unroll
;       for (int pr = 0; pr < 4; ++pr) {
;         const int ea = __builtin_amdgcn_readlane(evs, kb + 2 * pr), eb = __builtin_amdgcn_readlane(evs, kb + 2 * pr + 1);
;         const uint2* up = (const uint2*)(U + (size_t)(uphi ? eb : ea) * 768);
;         u6[3 * pr] = up[0]; u6[3 * pr + 1] = up[1]; u6[3 * pr + 2] = up[2];
;         v8[2 * pr] = *(const uint2*)(V + (size_t)ea * 512);
;         v8[2 * pr + 1] = *(const uint2*)(V + (size_t)eb * 512);
;       }
;     };
;     auto compute_batch = [&](const uint2 (&u6)[12], const uint2 (&v8)[8], int bt) {
;       const int kb = (bt & 7) * 8;
;       float dvec = 0.f;
; #pragma unroll
;       for (int pr = 0; pr < 4; ++pr) {
;         v6u_t qv; qv[0] = u6[3 * pr].x; qv[1] = u6[3 * pr].y; qv[2] = u6[3 * pr + 1].x; qv[3] = u6[3 * pr + 1].y; qv[4] = u6[3 * pr + 2].x; qv[5] = u6[3 * pr + 2].y;
;         const v32f_t wv = __builtin_amdgcn_cvt_scalef32_pk32_f32_fp6(qv, 1.0f);
;         f32x2 a2 = f32x2{0.f, 0.f};
; #pragma unroll
;         for (int i = 0; i < 16; ++i) a2 += f32x2{wv[2 * i], wv[2 * i + 1]} * xu[i];
;         float hs = a2.x + a2.y;
;         hs += dpp_row_shr(hs, 1); hs += dpp_row_shr(hs, 2); hs += dpp_row_shr(hs, 4); hs += dpp_row_shr(hs, 8);
;         hs += __builtin_bit_cast(float, __builtin_amdgcn_update_dpp(0, __builtin_bit_cast(int, hs), 0x142, 0xa, 0xf, false));
;         const float da = __builtin_bit_cast(float, __builtin_amdgcn_readlane(__builtin_bit_cast(int, hs), 31));
;         const float db = __builtin_bit_cast(float, __builtin_amdgcn_readlane(__builtin_bit_cast(int, hs), 63));
;         dvec = (lane == kb + 2 * pr) ? da : dvec;
;         dvec = (lane == kb + 2 * pr + 1) ? db : dvec;
;       }
.LBB0_22:
	s_ashr_i32 s61, s60, 31
	s_lshl_b64 s[50:51], s[60:61], 9
	s_ashr_i32 s55, s54, 31
	v_lshl_add_u64 v[0:1], v[76:77], 0, s[50:51]
	s_lshl_b64 s[50:51], s[54:55], 9
	s_ashr_i32 s59, s58, 31
	global_load_dwordx2 v[186:187], v[0:1], off
	v_lshl_add_u64 v[0:1], v[76:77], 0, s[50:51]
	s_lshl_b64 s[50:51], s[58:59], 9
	s_ashr_i32 s49, s48, 31
	global_load_dwordx2 v[184:185], v[0:1], off
	v_lshl_add_u64 v[0:1], v[76:77], 0, s[50:51]
	s_lshl_b64 s[48:49], s[48:49], 9
	s_ashr_i32 s57, s56, 31
	global_load_dwordx2 v[182:183], v[0:1], off
	v_lshl_add_u64 v[0:1], v[76:77], 0, s[48:49]
	s_lshl_b64 s[48:49], s[56:57], 9
	s_ashr_i32 s47, s46, 31
	global_load_dwordx2 v[180:181], v[0:1], off
	v_lshl_add_u64 v[0:1], v[76:77], 0, s[48:49]
	s_lshl_b64 s[46:47], s[46:47], 9
	s_ashr_i32 s53, s52, 31
	s_ashr_i32 s1, s0, 31
	global_load_dwordx2 v[174:175], v[0:1], off
	v_lshl_add_u64 v[0:1], v[76:77], 0, s[46:47]
	s_lshl_b64 s[46:47], s[52:53], 9
	s_lshl_b64 s[0:1], s[0:1], 9
	s_cmp_lt_u32 s6, 8
	s_cselect_b64 vcc, -1, 0
	global_load_dwordx2 v[172:173], v[0:1], off
	v_lshl_add_u64 v[0:1], v[76:77], 0, s[46:47]
	v_cndmask_b32_e32 v2, v90, v92, vcc
	s_add_i32 s51, s4, 1
	s_add_i32 s50, s4, 2
	global_load_dwordx2 v[170:171], v[0:1], off
	v_lshl_add_u64 v[0:1], v[76:77], 0, s[0:1]
	v_readlane_b32 s0, v2, s51
	v_readlane_b32 s48, v2, s50
	global_load_dwordx2 v[168:169], v[0:1], off
	v_mov_b32_e32 v0, s0
	v_mov_b32_e32 v1, s48
	s_ashr_i32 s1, s0, 31
	v_cndmask_b32_e64 v0, v0, v1, s[40:41]
	s_lshl_b64 s[0:1], s[0:1], 9
	s_ashr_i32 s49, s48, 31
	v_mad_i64_i32 v[166:167], s[52:53], v0, s42, v[74:75]
	v_lshl_add_u64 v[0:1], v[76:77], 0, s[0:1]
	s_lshl_b64 s[0:1], s[48:49], 9
	s_add_i32 s49, s4, 3
	s_add_i32 s47, s4, 4
	global_load_dwordx2 v[158:159], v[0:1], off
	v_lshl_add_u64 v[0:1], v[76:77], 0, s[0:1]
	v_readlane_b32 s0, v2, s49
	v_readlane_b32 s52, v2, s47
	global_load_dwordx2 v[156:157], v[0:1], off
	v_mov_b32_e32 v0, s0
	v_mov_b32_e32 v1, s52
	s_ashr_i32 s1, s0, 31
	v_cndmask_b32_e64 v0, v0, v1, s[40:41]
	s_lshl_b64 s[0:1], s[0:1], 9
	s_ashr_i32 s53, s52, 31
	v_mad_i64_i32 v[164:165], s[54:55], v0, s42, v[74:75]
	v_lshl_add_u64 v[0:1], v[76:77], 0, s[0:1]
	s_lshl_b64 s[0:1], s[52:53], 9
	s_add_i32 s37, s4, 5
	s_add_i32 s33, s4, 6
	global_load_dwordx2 v[154:155], v[0:1], off
	v_lshl_add_u64 v[0:1], v[76:77], 0, s[0:1]
	v_readlane_b32 s0, v2, s37
	v_readlane_b32 s52, v2, s33
	global_load_dwordx2 v[152:153], v[0:1], off
	v_mov_b32_e32 v0, s0
	v_mov_b32_e32 v1, s52
	s_ashr_i32 s1, s0, 31
	v_cndmask_b32_e64 v0, v0, v1, s[40:41]
	s_lshl_b64 s[0:1], s[0:1], 9
	s_ashr_i32 s53, s52, 31
	v_mad_i64_i32 v[162:163], s[54:55], v0, s42, v[74:75]
	v_lshl_add_u64 v[0:1], v[76:77], 0, s[0:1]
	s_lshl_b64 s[0:1], s[52:53], 9
	s_add_i32 s7, s4, 7
	s_add_i32 s5, s4, 8
	global_load_dwordx2 v[150:151], v[0:1], off
	v_lshl_add_u64 v[0:1], v[76:77], 0, s[0:1]
	v_readlane_b32 s0, v2, s7
	v_readlane_b32 s52, v2, s5
	global_load_dwordx2 v[148:149], v[0:1], off
	v_mov_b32_e32 v0, s0
	v_mov_b32_e32 v1, s52
	s_ashr_i32 s1, s0, 31
	v_cndmask_b32_e64 v0, v0, v1, s[40:41]
	s_lshl_b64 s[0:1], s[0:1], 9
	s_ashr_i32 s53, s52, 31
	v_mad_i64_i32 v[160:161], s[54:55], v0, s42, v[74:75]
	v_lshl_add_u64 v[0:1], v[76:77], 0, s[0:1]
	s_lshl_b64 s[0:1], s[52:53], 9
	global_load_dwordx2 v[146:147], v[0:1], off
	v_lshl_add_u64 v[0:1], v[76:77], 0, s[0:1]
	global_load_dwordx2 v[144:145], v[0:1], off
	global_load_dwordx2 v[200:201], v[166:167], off offset:16
	global_load_dwordx4 v[196:199], v[166:167], off
	global_load_dwordx2 v[232:233], v[164:165], off offset:16
	global_load_dwordx4 v[228:231], v[164:165], off
	global_load_dwordx2 v[238:239], v[162:163], off offset:16
	global_load_dwordx4 v[234:237], v[162:163], off
	global_load_dwordx2 v[244:245], v[160:161], off offset:16
	global_load_dwordx4 v[240:243], v[160:161], off
	s_waitcnt vmcnt(30)
	v_cvt_scalef32_pk32_f32_fp6 v[0:31], v[50:55], 1.0
	v_pk_fma_f32 v[0:1], v[0:1], v[96:97], 0 op_sel_hi:[1,1,0]
	s_add_i32 s46, s4, -7
	v_pk_fma_f32 v[0:1], v[2:3], v[98:99], v[0:1]
	s_and_b32 s48, s46, 48
	v_pk_fma_f32 v[0:1], v[4:5], v[100:101], v[0:1]
	v_cmp_eq_u32_e64 s[0:1], s48, v72
	v_pk_fma_f32 v[0:1], v[6:7], v[102:103], v[0:1]
	v_cndmask_b32_e32 v194, v190, v189, vcc
	v_pk_fma_f32 v[0:1], v[8:9], v[104:105], v[0:1]
	v_cndmask_b32_e32 v193, v192, v191, vcc
	v_pk_fma_f32 v[0:1], v[10:11], v[106:107], v[0:1]
	s_nop 0
	v_pk_fma_f32 v[0:1], v[12:13], v[108:109], v[0:1]
	s_nop 0
	v_pk_fma_f32 v[0:1], v[14:15], v[110:111], v[0:1]
	s_nop 0
	v_pk_fma_f32 v[0:1], v[16:17], v[112:113], v[0:1]
	s_nop 0
	v_pk_fma_f32 v[0:1], v[18:19], v[114:115], v[0:1]
	s_nop 0
	v_pk_fma_f32 v[0:1], v[20:21], v[116:117], v[0:1]
	s_nop 0
	v_pk_fma_f32 v[0:1], v[22:23], v[118:119], v[0:1]
	s_nop 0
	v_pk_fma_f32 v[0:1], v[24:25], v[120:121], v[0:1]
	s_nop 0
	v_pk_fma_f32 v[0:1], v[26:27], v[122:123], v[0:1]
	s_nop 0
	v_pk_fma_f32 v[0:1], v[28:29], v[124:125], v[0:1]
	s_nop 0
	v_pk_fma_f32 v[0:1], v[30:31], v[126:127], v[0:1]
	s_nop 0
	v_add_f32_e32 v0, v0, v1
	v_mov_b32_e32 v1, v177
	s_nop 0
	v_add_f32_dpp v0, v0, v0 row_shr:1 row_mask:0xf bank_mask:0xf bound_ctrl:1
	s_nop 1
	v_add_f32_dpp v0, v0, v0 row_shr:2 row_mask:0xf bank_mask:0xf bound_ctrl:1
	s_nop 1
	v_add_f32_dpp v0, v0, v0 row_shr:4 row_mask:0xf bank_mask:0xf bound_ctrl:1
	s_nop 1
	v_add_f32_dpp v0, v0, v0 row_shr:8 row_mask:0xf bank_mask:0xf bound_ctrl:1
	s_nop 1
	v_mov_b32_dpp v1, v0 row_bcast:15 row_mask:0xa bank_mask:0xf
	v_add_f32_e32 v0, v0, v1
	s_nop 0
	v_readlane_b32 s52, v0, 31
	v_readlane_b32 s53, v0, 63
	s_nop 0
	v_mov_b32_e32 v0, s52
	v_cndmask_b32_e64 v0, 0, v0, s[0:1]
	s_or_b32 s0, s48, 1
	v_cmp_eq_u32_e64 s[0:1], s0, v72
	v_mov_b32_e32 v1, s53
	s_nop 0
	v_cndmask_b32_e64 v50, v0, v1, s[0:1]
	s_waitcnt vmcnt(28)
; __device__ void peer_gather_phase(const Params& P, int l, bool do_store) {
;     ...
;       for (int pr = 0; pr < 4; ++pr) {
;         v6u_t qv; qv[0] = u6[3 * pr].x; qv[1] = u6[3 * pr].y; qv[2] = u6[3 * pr + 1].x; qv[3] = u6[3 * pr + 1].y; qv[4] = u6[3 * pr + 2].x; qv[5] = u6[3 * pr + 2].y;
;         const v32f_t wv = __builtin_amdgcn_cvt_scalef32_pk32_f32_fp6(qv, 1.0f);
;         f32x2 a2 = f32x2{0.f, 0.f};
; #pragma unroll
;         for (int i = 0; i < 16; ++i) a2 += f32x2{wv[2 * i], wv[2 * i + 1]} * xu[i];
;         float hs = a2.x + a2.y;
;         hs += dpp_row_shr(hs, 1); hs += dpp_row_shr(hs, 2); hs += dpp_row_shr(hs, 4); hs += dpp_row_shr(hs, 8);
;         hs += __builtin_bit_cast(float, __builtin_amdgcn_update_dpp(0, __builtin_bit_cast(int, hs), 0x142, 0xa, 0xf, false));
;         const float da = __builtin_bit_cast(float, __builtin_amdgcn_readlane(__builtin_bit_cast(int, hs), 31));
;         const float db = __builtin_bit_cast(float, __builtin_amdgcn_readlane(__builtin_bit_cast(int, hs), 63));
;         dvec = (lane == kb + 2 * pr) ? da : dvec;
;         dvec = (lane == kb + 2 * pr + 1) ? db : dvec;
;       }
	v_cvt_scalef32_pk32_f32_fp6 v[0:31], v[44:49], 1.0
	v_pk_fma_f32 v[0:1], v[0:1], v[96:97], 0 op_sel_hi:[1,1,0]
	s_or_b32 s0, s48, 2
	v_pk_fma_f32 v[0:1], v[2:3], v[98:99], v[0:1]
	v_cmp_eq_u32_e64 s[0:1], s0, v72
	v_pk_fma_f32 v[0:1], v[4:5], v[100:101], v[0:1]
	s_nop 0
	v_pk_fma_f32 v[0:1], v[6:7], v[102:103], v[0:1]
	s_nop 0
	v_pk_fma_f32 v[0:1], v[8:9], v[104:105], v[0:1]
	s_nop 0
	v_pk_fma_f32 v[0:1], v[10:11], v[106:107], v[0:1]
	s_nop 0
	v_pk_fma_f32 v[0:1], v[12:13], v[108:109], v[0:1]
	s_nop 0
	v_pk_fma_f32 v[0:1], v[14:15], v[110:111], v[0:1]
	s_nop 0
	v_pk_fma_f32 v[0:1], v[16:17], v[112:113], v[0:1]
	s_nop 0
	v_pk_fma_f32 v[0:1], v[18:19], v[114:115], v[0:1]
	s_nop 0
	v_pk_fma_f32 v[0:1], v[20:21], v[116:117], v[0:1]
	s_nop 0
	v_pk_fma_f32 v[0:1], v[22:23], v[118:119], v[0:1]
	s_nop 0
	v_pk_fma_f32 v[0:1], v[24:25], v[120:121], v[0:1]
	s_nop 0
	v_pk_fma_f32 v[0:1], v[26:27], v[122:123], v[0:1]
	s_nop 0
	v_pk_fma_f32 v[0:1], v[28:29], v[124:125], v[0:1]
	s_nop 0
	v_pk_fma_f32 v[0:1], v[30:31], v[126:127], v[0:1]
	s_nop 0
	v_add_f32_e32 v0, v0, v1
	v_mov_b32_e32 v1, v177
	s_nop 0
	v_add_f32_dpp v0, v0, v0 row_shr:1 row_mask:0xf bank_mask:0xf bound_ctrl:1
	s_nop 1
	v_add_f32_dpp v0, v0, v0 row_shr:2 row_mask:0xf bank_mask:0xf bound_ctrl:1
	s_nop 1
	v_add_f32_dpp v0, v0, v0 row_shr:4 row_mask:0xf bank_mask:0xf bound_ctrl:1
	s_nop 1
	v_add_f32_dpp v0, v0, v0 row_shr:8 row_mask:0xf bank_mask:0xf bound_ctrl:1
	s_nop 1
	v_mov_b32_dpp v1, v0 row_bcast:15 row_mask:0xa bank_mask:0xf
	v_add_f32_e32 v0, v0, v1
	s_nop 0
	v_readlane_b32 s52, v0, 31
	v_readlane_b32 s53, v0, 63
	s_nop 0
	v_mov_b32_e32 v0, s52
	v_cndmask_b32_e64 v0, v50, v0, s[0:1]
	s_or_b32 s0, s48, 3
	v_cmp_eq_u32_e64 s[0:1], s0, v72
	v_mov_b32_e32 v1, s53
	s_nop 0
	v_cndmask_b32_e64 v44, v0, v1, s[0:1]
	s_waitcnt vmcnt(26)
	v_cvt_scalef32_pk32_f32_fp6 v[0:31], v[38:43], 1.0
	v_pk_fma_f32 v[0:1], v[0:1], v[96:97], 0 op_sel_hi:[1,1,0]
	s_or_b32 s0, s48, 4
	v_pk_fma_f32 v[0:1], v[2:3], v[98:99], v[0:1]
	v_cmp_eq_u32_e64 s[0:1], s0, v72
	v_pk_fma_f32 v[0:1], v[4:5], v[100:101], v[0:1]
	s_nop 0
	v_pk_fma_f32 v[0:1], v[6:7], v[102:103], v[0:1]
	s_nop 0
	v_pk_fma_f32 v[0:1], v[8:9], v[104:105], v[0:1]
	s_nop 0
	v_pk_fma_f32 v[0:1], v[10:11], v[106:107], v[0:1]
	s_nop 0
	v_pk_fma_f32 v[0:1], v[12:13], v[108:109], v[0:1]
	s_nop 0
	v_pk_fma_f32 v[0:1], v[14:15], v[110:111], v[0:1]
	s_nop 0
	v_pk_fma_f32 v[0:1], v[16:17], v[112:113], v[0:1]
	s_nop 0
	v_pk_fma_f32 v[0:1], v[18:19], v[114:115], v[0:1]
	s_nop 0
	v_pk_fma_f32 v[0:1], v[20:21], v[116:117], v[0:1]
	s_nop 0
	v_pk_fma_f32 v[0:1], v[22:23], v[118:119], v[0:1]
	s_nop 0
	v_pk_fma_f32 v[0:1], v[24:25], v[120:121], v[0:1]
	s_nop 0
	v_pk_fma_f32 v[0:1], v[26:27], v[122:123], v[0:1]
	s_nop 0
	v_pk_fma_f32 v[0:1], v[28:29], v[124:125], v[0:1]
	s_nop 0
	v_pk_fma_f32 v[0:1], v[30:31], v[126:127], v[0:1]
	s_nop 0
	v_add_f32_e32 v0, v0, v1
	v_mov_b32_e32 v1, v177
	s_nop 0
	v_add_f32_dpp v0, v0, v0 row_shr:1 row_mask:0xf bank_mask:0xf bound_ctrl:1
	s_nop 1
	v_add_f32_dpp v0, v0, v0 row_shr:2 row_mask:0xf bank_mask:0xf bound_ctrl:1
	s_nop 1
	v_add_f32_dpp v0, v0, v0 row_shr:4 row_mask:0xf bank_mask:0xf bound_ctrl:1
	s_nop 1
	v_add_f32_dpp v0, v0, v0 row_shr:8 row_mask:0xf bank_mask:0xf bound_ctrl:1
	s_nop 1
	v_mov_b32_dpp v1, v0 row_bcast:15 row_mask:0xa bank_mask:0xf
	v_add_f32_e32 v0, v0, v1
	s_nop 0
	v_readlane_b32 s52, v0, 31
	v_readlane_b32 s53, v0, 63
	s_nop 0
	v_mov_b32_e32 v0, s52
	v_cndmask_b32_e64 v0, v44, v0, s[0:1]
	s_or_b32 s0, s48, 5
	v_cmp_eq_u32_e64 s[0:1], s0, v72
	v_mov_b32_e32 v1, s53
	s_nop 0
	v_cndmask_b32_e64 v38, v0, v1, s[0:1]
	s_waitcnt vmcnt(24)
	v_cvt_scalef32_pk32_f32_fp6 v[0:31], v[32:37], 1.0
	v_pk_fma_f32 v[0:1], v[0:1], v[96:97], 0 op_sel_hi:[1,1,0]
	s_or_b32 s0, s48, 6
	v_pk_fma_f32 v[0:1], v[2:3], v[98:99], v[0:1]
	v_cmp_eq_u32_e64 s[0:1], s0, v72
	v_pk_fma_f32 v[0:1], v[4:5], v[100:101], v[0:1]
	s_nop 0
	v_pk_fma_f32 v[0:1], v[6:7], v[102:103], v[0:1]
	s_nop 0
	v_pk_fma_f32 v[0:1], v[8:9], v[104:105], v[0:1]
	s_waitcnt vmcnt(23)
	v_cvt_scalef32_pk_f32_fp4 v[8:9], v187, 1.0
	v_pk_fma_f32 v[0:1], v[10:11], v[106:107], v[0:1]
	v_cvt_scalef32_pk_f32_fp4 v[10:11], v187, 1.0 op_sel:[1,0,0]
	v_pk_fma_f32 v[0:1], v[12:13], v[108:109], v[0:1]
	v_cvt_scalef32_pk_f32_fp4 v[12:13], v187, 1.0 op_sel:[0,1,0]
	v_pk_fma_f32 v[0:1], v[14:15], v[110:111], v[0:1]
	v_cvt_scalef32_pk_f32_fp4 v[14:15], v187, 1.0 op_sel:[1,1,0]
	v_pk_fma_f32 v[0:1], v[16:17], v[112:113], v[0:1]
	s_waitcnt vmcnt(22)
; __device__ void peer_gather_phase(const Params& P, int l, bool do_store) {
;     ...
;       const float sux = (bt < 8) ? sux0 : sux1;
;       const float gsx = (bt < 8) ? gsx0 : gsx1;
;       const float avec = gelu_t(dvec * sux) * gsx;
; #pragma unroll
;       for (int j = 0; j < 8; ++j) {
;         const float a = __builtin_bit_cast(float, __builtin_amdgcn_readlane(__builtin_bit_cast(int, avec), kb + j));
;         const f32x2 aa = f32x2{a, a};
;         y[0] += aa * __builtin_amdgcn_cvt_scalef32_pk_f32_fp4(v8[j].x, 1.0f, 0); y[1] += aa * __builtin_amdgcn_cvt_scalef32_pk_f32_fp4(v8[j].x, 1.0f, 1);
;         y[2] += aa * __builtin_amdgcn_cvt_scalef32_pk_f32_fp4(v8[j].x, 1.0f, 2); y[3] += aa * __builtin_amdgcn_cvt_scalef32_pk_f32_fp4(v8[j].x, 1.0f, 3);
;         y[4] += aa * __builtin_amdgcn_cvt_scalef32_pk_f32_fp4(v8[j].y, 1.0f, 0); y[5] += aa * __builtin_amdgcn_cvt_scalef32_pk_f32_fp4(v8[j].y, 1.0f, 1);
;         y[6] += aa * __builtin_amdgcn_cvt_scalef32_pk_f32_fp4(v8[j].y, 1.0f, 2); y[7] += aa * __builtin_amdgcn_cvt_scalef32_pk_f32_fp4(v8[j].y, 1.0f, 3);
;       }
	v_cvt_scalef32_pk_f32_fp4 v[16:17], v184, 1.0
	v_pk_fma_f32 v[0:1], v[18:19], v[114:115], v[0:1]
	s_nop 0
	v_pk_fma_f32 v[0:1], v[20:21], v[116:117], v[0:1]
	s_nop 0
	v_pk_fma_f32 v[0:1], v[22:23], v[118:119], v[0:1]
	s_nop 0
	v_pk_fma_f32 v[0:1], v[24:25], v[120:121], v[0:1]
	s_nop 0
	v_pk_fma_f32 v[0:1], v[26:27], v[122:123], v[0:1]
	s_nop 0
	v_pk_fma_f32 v[0:1], v[28:29], v[124:125], v[0:1]
	s_nop 0
	v_pk_fma_f32 v[0:1], v[30:31], v[126:127], v[0:1]
	s_nop 0
	v_add_f32_e32 v0, v0, v1
	v_mov_b32_e32 v1, v177
	s_nop 0
	v_add_f32_dpp v0, v0, v0 row_shr:1 row_mask:0xf bank_mask:0xf bound_ctrl:1
	s_nop 1
	v_add_f32_dpp v0, v0, v0 row_shr:2 row_mask:0xf bank_mask:0xf bound_ctrl:1
	s_nop 1
	v_add_f32_dpp v0, v0, v0 row_shr:4 row_mask:0xf bank_mask:0xf bound_ctrl:1
	s_nop 1
	v_add_f32_dpp v0, v0, v0 row_shr:8 row_mask:0xf bank_mask:0xf bound_ctrl:1
	s_nop 1
	v_mov_b32_dpp v1, v0 row_bcast:15 row_mask:0xa bank_mask:0xf
	v_add_f32_e32 v0, v0, v1
	s_nop 0
	v_readlane_b32 s52, v0, 31
	v_readlane_b32 s53, v0, 63
	s_nop 0
	v_mov_b32_e32 v0, s52
	v_cndmask_b32_e64 v0, v38, v0, s[0:1]
	s_or_b32 s0, s48, 7
	v_cmp_eq_u32_e64 s[0:1], s0, v72
	v_mov_b32_e32 v1, s53
	s_nop 0
	v_cndmask_b32_e64 v0, v0, v1, s[0:1]
	v_mul_f32_e32 v0, v194, v0
	v_mul_f32_e32 v1, 0x3d372713, v0
	v_mul_f32_e32 v1, v0, v1
	v_fma_f32 v1, v0, v1, v0
	v_mul_f32_e32 v1, 0x3f4c422a, v1
	v_add_f32_e32 v1, v1, v1
	v_mul_f32_e32 v1, 0x3fb8aa3b, v1
	v_exp_f32_e32 v1, v1
	v_mul_f32_e32 v0, 0.5, v0
	v_add_f32_e32 v1, 1.0, v1
	v_div_scale_f32 v2, s[0:1], v1, v1, 2.0
	v_rcp_f32_e32 v3, v2
	s_nop 0
	v_fma_f32 v4, -v2, v3, 1.0
	v_fmac_f32_e32 v3, v4, v3
	v_div_scale_f32 v4, vcc, 2.0, v1, 2.0
	v_mul_f32_e32 v5, v4, v3
	v_fma_f32 v6, -v2, v5, v4
	v_fmac_f32_e32 v5, v6, v3
	v_fma_f32 v2, -v2, v5, v4
	v_div_fmas_f32 v2, v2, v3, v5
	v_div_fixup_f32 v1, v2, v1, 2.0
	v_sub_f32_e32 v1, 1.0, v1
	v_add_f32_e32 v1, 1.0, v1
	v_mul_f32_e32 v0, v0, v1
	v_mul_f32_e32 v18, v193, v0
	v_cvt_scalef32_pk_f32_fp4 v[0:1], v186, 1.0
	v_readlane_b32 s0, v18, s46
	v_cvt_scalef32_pk_f32_fp4 v[2:3], v186, 1.0 op_sel:[1,0,0]
	v_cvt_scalef32_pk_f32_fp4 v[4:5], v186, 1.0 op_sel:[0,1,0]
	v_cvt_scalef32_pk_f32_fp4 v[6:7], v186, 1.0 op_sel:[1,1,0]
	v_pk_fma_f32 v[0:1], v[0:1], s[0:1], v[130:131] op_sel_hi:[1,0,1]
	v_pk_fma_f32 v[2:3], v[2:3], s[0:1], v[138:139] op_sel_hi:[1,0,1]
	v_pk_fma_f32 v[4:5], s[0:1], v[4:5], v[140:141] op_sel_hi:[0,1,1]
	v_pk_fma_f32 v[6:7], s[0:1], v[6:7], v[142:143] op_sel_hi:[0,1,1]
	v_pk_fma_f32 v[8:9], s[0:1], v[8:9], v[128:129] op_sel_hi:[0,1,1]
	v_pk_fma_f32 v[10:11], s[0:1], v[10:11], v[132:133] op_sel_hi:[0,1,1]
	v_pk_fma_f32 v[12:13], s[0:1], v[12:13], v[134:135] op_sel_hi:[0,1,1]
	v_pk_fma_f32 v[14:15], s[0:1], v[14:15], v[136:137] op_sel_hi:[0,1,1]
	s_add_i32 s0, s4, -6
	v_readlane_b32 s0, v18, s0
	s_nop 1
	v_pk_fma_f32 v[0:1], v[16:17], s[0:1], v[0:1] op_sel_hi:[1,0,1]
	v_cvt_scalef32_pk_f32_fp4 v[16:17], v184, 1.0 op_sel:[1,0,0]
	v_pk_fma_f32 v[2:3], v[16:17], s[0:1], v[2:3] op_sel_hi:[1,0,1]
	v_cvt_scalef32_pk_f32_fp4 v[16:17], v184, 1.0 op_sel:[0,1,0]
	v_pk_fma_f32 v[4:5], s[0:1], v[16:17], v[4:5] op_sel_hi:[0,1,1]
	v_cvt_scalef32_pk_f32_fp4 v[16:17], v184, 1.0 op_sel:[1,1,0]
	v_pk_fma_f32 v[6:7], s[0:1], v[16:17], v[6:7] op_sel_hi:[0,1,1]
	v_cvt_scalef32_pk_f32_fp4 v[16:17], v185, 1.0
	v_pk_fma_f32 v[8:9], s[0:1], v[16:17], v[8:9] op_sel_hi:[0,1,1]
	v_cvt_scalef32_pk_f32_fp4 v[16:17], v185, 1.0 op_sel:[1,0,0]
	v_pk_fma_f32 v[10:11], s[0:1], v[16:17], v[10:11] op_sel_hi:[0,1,1]
	v_cvt_scalef32_pk_f32_fp4 v[16:17], v185, 1.0 op_sel:[0,1,0]
	v_pk_fma_f32 v[12:13], s[0:1], v[16:17], v[12:13] op_sel_hi:[0,1,1]
	v_cvt_scalef32_pk_f32_fp4 v[16:17], v185, 1.0 op_sel:[1,1,0]
	v_pk_fma_f32 v[14:15], s[0:1], v[16:17], v[14:15] op_sel_hi:[0,1,1]
	s_add_i32 s0, s4, -5
	v_readlane_b32 s0, v18, s0
	s_waitcnt vmcnt(21)
	v_cvt_scalef32_pk_f32_fp4 v[16:17], v182, 1.0
	v_pk_fma_f32 v[0:1], v[16:17], s[0:1], v[0:1] op_sel_hi:[1,0,1]
	v_cvt_scalef32_pk_f32_fp4 v[16:17], v182, 1.0 op_sel:[1,0,0]
	v_pk_fma_f32 v[2:3], v[16:17], s[0:1], v[2:3] op_sel_hi:[1,0,1]
	v_cvt_scalef32_pk_f32_fp4 v[16:17], v182, 1.0 op_sel:[0,1,0]
	v_pk_fma_f32 v[4:5], s[0:1], v[16:17], v[4:5] op_sel_hi:[0,1,1]
	v_cvt_scalef32_pk_f32_fp4 v[16:17], v182, 1.0 op_sel:[1,1,0]
	v_pk_fma_f32 v[6:7], s[0:1], v[16:17], v[6:7] op_sel_hi:[0,1,1]
	v_cvt_scalef32_pk_f32_fp4 v[16:17], v183, 1.0
	v_pk_fma_f32 v[8:9], s[0:1], v[16:17], v[8:9] op_sel_hi:[0,1,1]
	v_cvt_scalef32_pk_f32_fp4 v[16:17], v183, 1.0 op_sel:[1,0,0]
	v_pk_fma_f32 v[10:11], s[0:1], v[16:17], v[10:11] op_sel_hi:[0,1,1]
	v_cvt_scalef32_pk_f32_fp4 v[16:17], v183, 1.0 op_sel:[0,1,0]
	v_pk_fma_f32 v[12:13], s[0:1], v[16:17], v[12:13] op_sel_hi:[0,1,1]
	v_cvt_scalef32_pk_f32_fp4 v[16:17], v183, 1.0 op_sel:[1,1,0]
	v_pk_fma_f32 v[14:15], s[0:1], v[16:17], v[14:15] op_sel_hi:[0,1,1]
	s_add_i32 s0, s4, -4
	v_readlane_b32 s0, v18, s0
	s_waitcnt vmcnt(20)
	v_cvt_scalef32_pk_f32_fp4 v[16:17], v180, 1.0
	v_pk_fma_f32 v[0:1], v[16:17], s[0:1], v[0:1] op_sel_hi:[1,0,1]
	v_cvt_scalef32_pk_f32_fp4 v[16:17], v180, 1.0 op_sel:[1,0,0]
	v_pk_fma_f32 v[2:3], v[16:17], s[0:1], v[2:3] op_sel_hi:[1,0,1]
	v_cvt_scalef32_pk_f32_fp4 v[16:17], v180, 1.0 op_sel:[0,1,0]
	v_pk_fma_f32 v[4:5], s[0:1], v[16:17], v[4:5] op_sel_hi:[0,1,1]
	v_cvt_scalef32_pk_f32_fp4 v[16:17], v180, 1.0 op_sel:[1,1,0]
	v_pk_fma_f32 v[6:7], s[0:1], v[16:17], v[6:7] op_sel_hi:[0,1,1]
	v_cvt_scalef32_pk_f32_fp4 v[16:17], v181, 1.0
	v_pk_fma_f32 v[8:9], s[0:1], v[16:17], v[8:9] op_sel_hi:[0,1,1]
	v_cvt_scalef32_pk_f32_fp4 v[16:17], v181, 1.0 op_sel:[1,0,0]
	v_pk_fma_f32 v[10:11], s[0:1], v[16:17], v[10:11] op_sel_hi:[0,1,1]
	v_cvt_scalef32_pk_f32_fp4 v[16:17], v181, 1.0 op_sel:[0,1,0]
	v_pk_fma_f32 v[12:13], s[0:1], v[16:17], v[12:13] op_sel_hi:[0,1,1]
	v_cvt_scalef32_pk_f32_fp4 v[16:17], v181, 1.0 op_sel:[1,1,0]
	v_pk_fma_f32 v[14:15], s[0:1], v[16:17], v[14:15] op_sel_hi:[0,1,1]
	s_add_i32 s0, s4, -3
	v_readlane_b32 s0, v18, s0
	s_waitcnt vmcnt(19)
; __device__ void peer_gather_phase(const Params& P, int l, bool do_store) {
;     ...
; #pragma unroll
;       for (int j = 0; j < 8; ++j) {
;         const float a = __builtin_bit_cast(float, __builtin_amdgcn_readlane(__builtin_bit_cast(int, avec), kb + j));
;         const f32x2 aa = f32x2{a, a};
;         y[0] += aa * __builtin_amdgcn_cvt_scalef32_pk_f32_fp4(v8[j].x, 1.0f, 0); y[1] += aa * __builtin_amdgcn_cvt_scalef32_pk_f32_fp4(v8[j].x, 1.0f, 1);
;         y[2] += aa * __builtin_amdgcn_cvt_scalef32_pk_f32_fp4(v8[j].x, 1.0f, 2); y[3] += aa * __builtin_amdgcn_cvt_scalef32_pk_f32_fp4(v8[j].x, 1.0f, 3);
;         y[4] += aa * __builtin_amdgcn_cvt_scalef32_pk_f32_fp4(v8[j].y, 1.0f, 0); y[5] += aa * __builtin_amdgcn_cvt_scalef32_pk_f32_fp4(v8[j].y, 1.0f, 1);
;         y[6] += aa * __builtin_amdgcn_cvt_scalef32_pk_f32_fp4(v8[j].y, 1.0f, 2); y[7] += aa * __builtin_amdgcn_cvt_scalef32_pk_f32_fp4(v8[j].y, 1.0f, 3);
;       }
;     };
;     load_batch(uA, vA, 0);
; #pragma unroll 1
;     for (int bt = 0; bt < 16; bt += 2) {
;       load_batch(uB, vB, bt + 1);
;       compute_batch(uA, vA, bt);
;       load_batch(uA, vA, (bt + 2 < 16) ? bt + 2 : 15);
	v_cvt_scalef32_pk_f32_fp4 v[16:17], v174, 1.0
	v_pk_fma_f32 v[0:1], v[16:17], s[0:1], v[0:1] op_sel_hi:[1,0,1]
	v_cvt_scalef32_pk_f32_fp4 v[16:17], v174, 1.0 op_sel:[1,0,0]
	v_pk_fma_f32 v[2:3], v[16:17], s[0:1], v[2:3] op_sel_hi:[1,0,1]
	v_cvt_scalef32_pk_f32_fp4 v[16:17], v174, 1.0 op_sel:[0,1,0]
	v_pk_fma_f32 v[4:5], s[0:1], v[16:17], v[4:5] op_sel_hi:[0,1,1]
	v_cvt_scalef32_pk_f32_fp4 v[16:17], v174, 1.0 op_sel:[1,1,0]
	v_pk_fma_f32 v[6:7], s[0:1], v[16:17], v[6:7] op_sel_hi:[0,1,1]
	v_cvt_scalef32_pk_f32_fp4 v[16:17], v175, 1.0
	v_pk_fma_f32 v[8:9], s[0:1], v[16:17], v[8:9] op_sel_hi:[0,1,1]
	v_cvt_scalef32_pk_f32_fp4 v[16:17], v175, 1.0 op_sel:[1,0,0]
	v_pk_fma_f32 v[10:11], s[0:1], v[16:17], v[10:11] op_sel_hi:[0,1,1]
	v_cvt_scalef32_pk_f32_fp4 v[16:17], v175, 1.0 op_sel:[0,1,0]
	v_pk_fma_f32 v[12:13], s[0:1], v[16:17], v[12:13] op_sel_hi:[0,1,1]
	v_cvt_scalef32_pk_f32_fp4 v[16:17], v175, 1.0 op_sel:[1,1,0]
	v_pk_fma_f32 v[14:15], s[0:1], v[16:17], v[14:15] op_sel_hi:[0,1,1]
	s_add_i32 s0, s4, -2
	v_readlane_b32 s0, v18, s0
	s_waitcnt vmcnt(18)
	v_cvt_scalef32_pk_f32_fp4 v[16:17], v172, 1.0
	v_pk_fma_f32 v[0:1], v[16:17], s[0:1], v[0:1] op_sel_hi:[1,0,1]
	v_cvt_scalef32_pk_f32_fp4 v[16:17], v172, 1.0 op_sel:[1,0,0]
	v_pk_fma_f32 v[2:3], v[16:17], s[0:1], v[2:3] op_sel_hi:[1,0,1]
	v_cvt_scalef32_pk_f32_fp4 v[16:17], v172, 1.0 op_sel:[0,1,0]
	v_pk_fma_f32 v[4:5], s[0:1], v[16:17], v[4:5] op_sel_hi:[0,1,1]
	v_cvt_scalef32_pk_f32_fp4 v[16:17], v172, 1.0 op_sel:[1,1,0]
	v_pk_fma_f32 v[6:7], s[0:1], v[16:17], v[6:7] op_sel_hi:[0,1,1]
	v_cvt_scalef32_pk_f32_fp4 v[16:17], v173, 1.0
	v_pk_fma_f32 v[8:9], s[0:1], v[16:17], v[8:9] op_sel_hi:[0,1,1]
	v_cvt_scalef32_pk_f32_fp4 v[16:17], v173, 1.0 op_sel:[1,0,0]
	v_pk_fma_f32 v[10:11], s[0:1], v[16:17], v[10:11] op_sel_hi:[0,1,1]
	v_cvt_scalef32_pk_f32_fp4 v[16:17], v173, 1.0 op_sel:[0,1,0]
	v_pk_fma_f32 v[12:13], s[0:1], v[16:17], v[12:13] op_sel_hi:[0,1,1]
	v_cvt_scalef32_pk_f32_fp4 v[16:17], v173, 1.0 op_sel:[1,1,0]
	v_pk_fma_f32 v[14:15], s[0:1], v[16:17], v[14:15] op_sel_hi:[0,1,1]
	s_add_i32 s0, s4, -1
	v_readlane_b32 s0, v18, s0
	s_waitcnt vmcnt(17)
	v_cvt_scalef32_pk_f32_fp4 v[16:17], v170, 1.0
	v_pk_fma_f32 v[0:1], v[16:17], s[0:1], v[0:1] op_sel_hi:[1,0,1]
	v_cvt_scalef32_pk_f32_fp4 v[16:17], v170, 1.0 op_sel:[1,0,0]
	v_pk_fma_f32 v[2:3], v[16:17], s[0:1], v[2:3] op_sel_hi:[1,0,1]
	v_cvt_scalef32_pk_f32_fp4 v[16:17], v170, 1.0 op_sel:[0,1,0]
	v_pk_fma_f32 v[4:5], s[0:1], v[16:17], v[4:5] op_sel_hi:[0,1,1]
	v_cvt_scalef32_pk_f32_fp4 v[16:17], v170, 1.0 op_sel:[1,1,0]
	v_pk_fma_f32 v[6:7], s[0:1], v[16:17], v[6:7] op_sel_hi:[0,1,1]
	v_cvt_scalef32_pk_f32_fp4 v[16:17], v171, 1.0
	v_pk_fma_f32 v[8:9], s[0:1], v[16:17], v[8:9] op_sel_hi:[0,1,1]
	v_cvt_scalef32_pk_f32_fp4 v[16:17], v171, 1.0 op_sel:[1,0,0]
	v_pk_fma_f32 v[10:11], s[0:1], v[16:17], v[10:11] op_sel_hi:[0,1,1]
	v_cvt_scalef32_pk_f32_fp4 v[16:17], v171, 1.0 op_sel:[0,1,0]
	v_pk_fma_f32 v[12:13], s[0:1], v[16:17], v[12:13] op_sel_hi:[0,1,1]
	v_cvt_scalef32_pk_f32_fp4 v[16:17], v171, 1.0 op_sel:[1,1,0]
	v_pk_fma_f32 v[14:15], s[0:1], v[16:17], v[14:15] op_sel_hi:[0,1,1]
	v_readlane_b32 s0, v18, s4
	s_waitcnt vmcnt(16)
	v_cvt_scalef32_pk_f32_fp4 v[16:17], v168, 1.0
	v_pk_fma_f32 v[128:129], v[16:17], s[0:1], v[0:1] op_sel_hi:[1,0,1]
	v_cvt_scalef32_pk_f32_fp4 v[0:1], v168, 1.0 op_sel:[1,0,0]
	v_pk_fma_f32 v[130:131], v[0:1], s[0:1], v[2:3] op_sel_hi:[1,0,1]
	v_cvt_scalef32_pk_f32_fp4 v[0:1], v168, 1.0 op_sel:[0,1,0]
	v_pk_fma_f32 v[132:133], s[0:1], v[0:1], v[4:5] op_sel_hi:[0,1,1]
	v_cvt_scalef32_pk_f32_fp4 v[0:1], v168, 1.0 op_sel:[1,1,0]
	v_pk_fma_f32 v[134:135], s[0:1], v[0:1], v[6:7] op_sel_hi:[0,1,1]
	v_cvt_scalef32_pk_f32_fp4 v[0:1], v169, 1.0
	v_pk_fma_f32 v[136:137], s[0:1], v[0:1], v[8:9] op_sel_hi:[0,1,1]
	v_cvt_scalef32_pk_f32_fp4 v[0:1], v169, 1.0 op_sel:[1,0,0]
	v_pk_fma_f32 v[138:139], s[0:1], v[0:1], v[10:11] op_sel_hi:[0,1,1]
	v_cvt_scalef32_pk_f32_fp4 v[0:1], v169, 1.0 op_sel:[0,1,0]
	v_pk_fma_f32 v[140:141], s[0:1], v[0:1], v[12:13] op_sel_hi:[0,1,1]
	v_cvt_scalef32_pk_f32_fp4 v[0:1], v169, 1.0 op_sel:[1,1,0]
	v_pk_fma_f32 v[142:143], s[0:1], v[0:1], v[14:15] op_sel_hi:[0,1,1]
	s_add_i32 s1, s6, 2
	s_cmp_lt_u32 s6, 14
	s_cselect_b32 s0, s1, 15
	s_cmp_lt_u32 s0, 8
	s_cselect_b64 vcc, -1, 0
	s_lshl_b32 s0, s0, 3
	s_or_b32 s46, s0, 1
	v_cndmask_b32_e32 v2, v90, v92, vcc
	s_or_b32 s48, s0, 2
	v_readlane_b32 s60, v2, s0
	v_readlane_b32 s54, v2, s46
	s_or_b32 s52, s0, 3
	v_mov_b32_e32 v0, s60
	v_mov_b32_e32 v1, s54
	v_cndmask_b32_e64 v0, v0, v1, s[40:41]
	v_mad_i64_i32 v[0:1], s[98:99], v0, s42, v[74:75]
	v_readlane_b32 s58, v2, s48
	v_readlane_b32 s48, v2, s52
	global_load_dwordx2 v[54:55], v[0:1], off offset:16
	global_load_dwordx4 v[50:53], v[0:1], off
	v_mov_b32_e32 v0, s58
	v_mov_b32_e32 v1, s48
	s_or_b32 s56, s0, 4
	s_or_b32 s65, s0, 5
	v_cndmask_b32_e64 v0, v0, v1, s[40:41]
	v_mad_i64_i32 v[0:1], s[98:99], v0, s42, v[74:75]
	v_readlane_b32 s56, v2, s56
	v_readlane_b32 s46, v2, s65
	global_load_dwordx2 v[48:49], v[0:1], off offset:16
	global_load_dwordx4 v[44:47], v[0:1], off
	v_mov_b32_e32 v0, s56
	v_mov_b32_e32 v1, s46
	s_or_b32 s67, s0, 6
	s_or_b32 s96, s0, 7
	v_cndmask_b32_e64 v0, v0, v1, s[40:41]
	v_mad_i64_i32 v[0:1], s[98:99], v0, s42, v[74:75]
	v_readlane_b32 s52, v2, s67
	v_readlane_b32 s0, v2, s96
	global_load_dwordx2 v[42:43], v[0:1], off offset:16
	global_load_dwordx4 v[38:41], v[0:1], off
	v_mov_b32_e32 v0, s52
	v_mov_b32_e32 v1, s0
	v_cndmask_b32_e64 v0, v0, v1, s[40:41]
	v_mad_i64_i32 v[0:1], s[98:99], v0, s42, v[74:75]
	global_load_dwordx2 v[36:37], v[0:1], off offset:16
	global_load_dwordx4 v[32:35], v[0:1], off
	s_and_b32 s64, s51, 56
	s_or_b32 s63, s64, 1
	s_or_b32 s62, s64, 2
	s_or_b32 s61, s64, 3
	s_or_b32 s59, s64, 4
	s_or_b32 s57, s64, 5
	s_or_b32 s55, s64, 6
	s_or_b32 s53, s64, 7
	s_add_i32 s4, s4, 16
	s_cmp_gt_u32 s6, 13
	v_cmp_eq_u32_e32 vcc, s64, v72
	s_waitcnt vmcnt(14)
; __device__ void peer_gather_phase(const Params& P, int l, bool do_store) {
;     ...
;       for (int pr = 0; pr < 4; ++pr) {
;         v6u_t qv; qv[0] = u6[3 * pr].x; qv[1] = u6[3 * pr].y; qv[2] = u6[3 * pr + 1].x; qv[3] = u6[3 * pr + 1].y; qv[4] = u6[3 * pr + 2].x; qv[5] = u6[3 * pr + 2].y;
;         const v32f_t wv = __builtin_amdgcn_cvt_scalef32_pk32_f32_fp6(qv, 1.0f);
;         f32x2 a2 = f32x2{0.f, 0.f};
; #pragma unroll
;         for (int i = 0; i < 16; ++i) a2 += f32x2{wv[2 * i], wv[2 * i + 1]} * xu[i];
;         float hs = a2.x + a2.y;
;         hs += dpp_row_shr(hs, 1); hs += dpp_row_shr(hs, 2); hs += dpp_row_shr(hs, 4); hs += dpp_row_shr(hs, 8);
;         hs += __builtin_bit_cast(float, __builtin_amdgcn_update_dpp(0, __builtin_bit_cast(int, hs), 0x142, 0xa, 0xf, false));
;         const float da = __builtin_bit_cast(float, __builtin_amdgcn_readlane(__builtin_bit_cast(int, hs), 31));
;         const float db = __builtin_bit_cast(float, __builtin_amdgcn_readlane(__builtin_bit_cast(int, hs), 63));
;         dvec = (lane == kb + 2 * pr) ? da : dvec;
;         dvec = (lane == kb + 2 * pr + 1) ? db : dvec;
;       }
	v_cvt_scalef32_pk32_f32_fp6 v[0:31], v[196:201], 1.0
	v_pk_fma_f32 v[0:1], v[0:1], v[96:97], 0 op_sel_hi:[1,1,0]
	s_nop 0
	v_pk_fma_f32 v[0:1], v[2:3], v[98:99], v[0:1]
	s_nop 0
	v_pk_fma_f32 v[0:1], v[4:5], v[100:101], v[0:1]
	s_nop 0
	v_pk_fma_f32 v[0:1], v[6:7], v[102:103], v[0:1]
	s_nop 0
	v_pk_fma_f32 v[0:1], v[8:9], v[104:105], v[0:1]
	s_nop 0
	v_pk_fma_f32 v[0:1], v[10:11], v[106:107], v[0:1]
	s_nop 0
	v_pk_fma_f32 v[0:1], v[12:13], v[108:109], v[0:1]
	s_nop 0
	v_pk_fma_f32 v[0:1], v[14:15], v[110:111], v[0:1]
	s_nop 0
	v_pk_fma_f32 v[0:1], v[16:17], v[112:113], v[0:1]
	s_nop 0
	v_pk_fma_f32 v[0:1], v[18:19], v[114:115], v[0:1]
	s_nop 0
	v_pk_fma_f32 v[0:1], v[20:21], v[116:117], v[0:1]
	s_nop 0
	v_pk_fma_f32 v[0:1], v[22:23], v[118:119], v[0:1]
	s_nop 0
	v_pk_fma_f32 v[0:1], v[24:25], v[120:121], v[0:1]
	s_nop 0
	v_pk_fma_f32 v[0:1], v[26:27], v[122:123], v[0:1]
	s_nop 0
	v_pk_fma_f32 v[0:1], v[28:29], v[124:125], v[0:1]
	s_nop 0
	v_pk_fma_f32 v[0:1], v[30:31], v[126:127], v[0:1]
	s_nop 0
	v_add_f32_e32 v0, v0, v1
	v_mov_b32_e32 v1, v177
	s_nop 0
	v_add_f32_dpp v0, v0, v0 row_shr:1 row_mask:0xf bank_mask:0xf bound_ctrl:1
	s_nop 1
	v_add_f32_dpp v0, v0, v0 row_shr:2 row_mask:0xf bank_mask:0xf bound_ctrl:1
	s_nop 1
	v_add_f32_dpp v0, v0, v0 row_shr:4 row_mask:0xf bank_mask:0xf bound_ctrl:1
	s_nop 1
	v_add_f32_dpp v0, v0, v0 row_shr:8 row_mask:0xf bank_mask:0xf bound_ctrl:1
	s_nop 1
	v_mov_b32_dpp v1, v0 row_bcast:15 row_mask:0xa bank_mask:0xf
	v_add_f32_e32 v0, v0, v1
	s_nop 0
	v_readlane_b32 s6, v0, 31
	v_readlane_b32 s65, v0, 63
	s_nop 0
	v_mov_b32_e32 v0, s6
	v_cndmask_b32_e32 v0, 0, v0, vcc
	v_cmp_eq_u32_e32 vcc, s63, v72
	v_mov_b32_e32 v1, s65
	s_nop 0
	v_cndmask_b32_e32 v170, v0, v1, vcc
	v_cmp_eq_u32_e32 vcc, s62, v72
	s_waitcnt vmcnt(12)
	v_cvt_scalef32_pk32_f32_fp6 v[0:31], v[228:233], 1.0
	v_pk_fma_f32 v[0:1], v[0:1], v[96:97], 0 op_sel_hi:[1,1,0]
	s_nop 0
	v_pk_fma_f32 v[0:1], v[2:3], v[98:99], v[0:1]
	s_nop 0
	v_pk_fma_f32 v[0:1], v[4:5], v[100:101], v[0:1]
	s_nop 0
	v_pk_fma_f32 v[0:1], v[6:7], v[102:103], v[0:1]
	s_nop 0
	v_pk_fma_f32 v[0:1], v[8:9], v[104:105], v[0:1]
	s_nop 0
	v_pk_fma_f32 v[0:1], v[10:11], v[106:107], v[0:1]
	s_nop 0
	v_pk_fma_f32 v[0:1], v[12:13], v[108:109], v[0:1]
	s_nop 0
	v_pk_fma_f32 v[0:1], v[14:15], v[110:111], v[0:1]
	s_nop 0
	v_pk_fma_f32 v[0:1], v[16:17], v[112:113], v[0:1]
	s_nop 0
	v_pk_fma_f32 v[0:1], v[18:19], v[114:115], v[0:1]
	s_nop 0
	v_pk_fma_f32 v[0:1], v[20:21], v[116:117], v[0:1]
	s_nop 0
	v_pk_fma_f32 v[0:1], v[22:23], v[118:119], v[0:1]
	s_nop 0
	v_pk_fma_f32 v[0:1], v[24:25], v[120:121], v[0:1]
	s_nop 0
	v_pk_fma_f32 v[0:1], v[26:27], v[122:123], v[0:1]
	s_nop 0
	v_pk_fma_f32 v[0:1], v[28:29], v[124:125], v[0:1]
	s_nop 0
	v_pk_fma_f32 v[0:1], v[30:31], v[126:127], v[0:1]
	s_nop 0
	v_add_f32_e32 v0, v0, v1
	v_mov_b32_e32 v1, v177
	s_nop 0
	v_add_f32_dpp v0, v0, v0 row_shr:1 row_mask:0xf bank_mask:0xf bound_ctrl:1
	s_nop 1
	v_add_f32_dpp v0, v0, v0 row_shr:2 row_mask:0xf bank_mask:0xf bound_ctrl:1
	s_nop 1
	v_add_f32_dpp v0, v0, v0 row_shr:4 row_mask:0xf bank_mask:0xf bound_ctrl:1
	s_nop 1
	v_add_f32_dpp v0, v0, v0 row_shr:8 row_mask:0xf bank_mask:0xf bound_ctrl:1
	s_nop 1
	v_mov_b32_dpp v1, v0 row_bcast:15 row_mask:0xa bank_mask:0xf
	v_add_f32_e32 v0, v0, v1
	s_nop 0
	v_readlane_b32 s6, v0, 31
	v_readlane_b32 s63, v0, 63
	s_nop 0
	v_mov_b32_e32 v0, s6
	v_cndmask_b32_e32 v0, v170, v0, vcc
	v_cmp_eq_u32_e32 vcc, s61, v72
	v_mov_b32_e32 v1, s63
	s_nop 0
	v_cndmask_b32_e32 v168, v0, v1, vcc
	v_cmp_eq_u32_e32 vcc, s59, v72
	s_waitcnt vmcnt(10)
	v_cvt_scalef32_pk32_f32_fp6 v[0:31], v[234:239], 1.0
	v_pk_fma_f32 v[0:1], v[0:1], v[96:97], 0 op_sel_hi:[1,1,0]
	s_nop 0
	v_pk_fma_f32 v[0:1], v[2:3], v[98:99], v[0:1]
	s_nop 0
	v_pk_fma_f32 v[0:1], v[4:5], v[100:101], v[0:1]
	s_nop 0
	v_pk_fma_f32 v[0:1], v[6:7], v[102:103], v[0:1]
	s_nop 0
	v_pk_fma_f32 v[0:1], v[8:9], v[104:105], v[0:1]
	s_nop 0
	v_pk_fma_f32 v[0:1], v[10:11], v[106:107], v[0:1]
	s_nop 0
	v_pk_fma_f32 v[0:1], v[12:13], v[108:109], v[0:1]
	s_nop 0
	v_pk_fma_f32 v[0:1], v[14:15], v[110:111], v[0:1]
	s_nop 0
	v_pk_fma_f32 v[0:1], v[16:17], v[112:113], v[0:1]
	s_nop 0
	v_pk_fma_f32 v[0:1], v[18:19], v[114:115], v[0:1]
	s_nop 0
	v_pk_fma_f32 v[0:1], v[20:21], v[116:117], v[0:1]
	s_nop 0
	v_pk_fma_f32 v[0:1], v[22:23], v[118:119], v[0:1]
	s_nop 0
	v_pk_fma_f32 v[0:1], v[24:25], v[120:121], v[0:1]
	s_nop 0
	v_pk_fma_f32 v[0:1], v[26:27], v[122:123], v[0:1]
	s_nop 0
	v_pk_fma_f32 v[0:1], v[28:29], v[124:125], v[0:1]
	s_nop 0
	v_pk_fma_f32 v[0:1], v[30:31], v[126:127], v[0:1]
	s_nop 0
	v_add_f32_e32 v0, v0, v1
	v_mov_b32_e32 v1, v177
	s_nop 0
	v_add_f32_dpp v0, v0, v0 row_shr:1 row_mask:0xf bank_mask:0xf bound_ctrl:1
	s_nop 1
	v_add_f32_dpp v0, v0, v0 row_shr:2 row_mask:0xf bank_mask:0xf bound_ctrl:1
	s_nop 1
	v_add_f32_dpp v0, v0, v0 row_shr:4 row_mask:0xf bank_mask:0xf bound_ctrl:1
	s_nop 1
	v_add_f32_dpp v0, v0, v0 row_shr:8 row_mask:0xf bank_mask:0xf bound_ctrl:1
	s_nop 1
	v_mov_b32_dpp v1, v0 row_bcast:15 row_mask:0xa bank_mask:0xf
	v_add_f32_e32 v0, v0, v1
	s_nop 0
	v_readlane_b32 s6, v0, 31
	v_readlane_b32 s61, v0, 63
	s_nop 0
	v_mov_b32_e32 v0, s6
	v_cndmask_b32_e32 v0, v168, v0, vcc
	v_cmp_eq_u32_e32 vcc, s57, v72
	v_mov_b32_e32 v1, s61
	s_nop 0
	v_cndmask_b32_e32 v166, v0, v1, vcc
	v_cmp_eq_u32_e32 vcc, s55, v72
	s_waitcnt vmcnt(8)
; __device__ void peer_gather_phase(const Params& P, int l, bool do_store) {
;     ...
;       for (int pr = 0; pr < 4; ++pr) {
;         v6u_t qv; qv[0] = u6[3 * pr].x; qv[1] = u6[3 * pr].y; qv[2] = u6[3 * pr + 1].x; qv[3] = u6[3 * pr + 1].y; qv[4] = u6[3 * pr + 2].x; qv[5] = u6[3 * pr + 2].y;
;         const v32f_t wv = __builtin_amdgcn_cvt_scalef32_pk32_f32_fp6(qv, 1.0f);
;         f32x2 a2 = f32x2{0.f, 0.f};
; #pragma unroll
;         for (int i = 0; i < 16; ++i) a2 += f32x2{wv[2 * i], wv[2 * i + 1]} * xu[i];
;         float hs = a2.x + a2.y;
;         hs += dpp_row_shr(hs, 1); hs += dpp_row_shr(hs, 2); hs += dpp_row_shr(hs, 4); hs += dpp_row_shr(hs, 8);
;         hs += __builtin_bit_cast(float, __builtin_amdgcn_update_dpp(0, __builtin_bit_cast(int, hs), 0x142, 0xa, 0xf, false));
;         const float da = __builtin_bit_cast(float, __builtin_amdgcn_readlane(__builtin_bit_cast(int, hs), 31));
;         const float db = __builtin_bit_cast(float, __builtin_amdgcn_readlane(__builtin_bit_cast(int, hs), 63));
;         dvec = (lane == kb + 2 * pr) ? da : dvec;
;         dvec = (lane == kb + 2 * pr + 1) ? db : dvec;
;       }
;       const float sux = (bt < 8) ? sux0 : sux1;
;       const float gsx = (bt < 8) ? gsx0 : gsx1;
;       const float avec = gelu_t(dvec * sux) * gsx;
; #pragma unroll
;       for (int j = 0; j < 8; ++j) {
;         const float a = __builtin_bit_cast(float, __builtin_amdgcn_readlane(__builtin_bit_cast(int, avec), kb + j));
;         const f32x2 aa = f32x2{a, a};
;         y[0] += aa * __builtin_amdgcn_cvt_scalef32_pk_f32_fp4(v8[j].x, 1.0f, 0); y[1] += aa * __builtin_amdgcn_cvt_scalef32_pk_f32_fp4(v8[j].x, 1.0f, 1);
;         y[2] += aa * __builtin_amdgcn_cvt_scalef32_pk_f32_fp4(v8[j].x, 1.0f, 2); y[3] += aa * __builtin_amdgcn_cvt_scalef32_pk_f32_fp4(v8[j].x, 1.0f, 3);
;         y[4] += aa * __builtin_amdgcn_cvt_scalef32_pk_f32_fp4(v8[j].y, 1.0f, 0); y[5] += aa * __builtin_amdgcn_cvt_scalef32_pk_f32_fp4(v8[j].y, 1.0f, 1);
;         y[6] += aa * __builtin_amdgcn_cvt_scalef32_pk_f32_fp4(v8[j].y, 1.0f, 2); y[7] += aa * __builtin_amdgcn_cvt_scalef32_pk_f32_fp4(v8[j].y, 1.0f, 3);
;       }
	v_cvt_scalef32_pk32_f32_fp6 v[0:31], v[240:245], 1.0
	v_pk_fma_f32 v[0:1], v[0:1], v[96:97], 0 op_sel_hi:[1,1,0]
	s_nop 0
	v_pk_fma_f32 v[0:1], v[2:3], v[98:99], v[0:1]
	s_nop 0
	v_pk_fma_f32 v[0:1], v[4:5], v[100:101], v[0:1]
	s_nop 0
	v_pk_fma_f32 v[0:1], v[6:7], v[102:103], v[0:1]
	s_nop 0
	v_pk_fma_f32 v[0:1], v[8:9], v[104:105], v[0:1]
	v_cvt_scalef32_pk_f32_fp4 v[8:9], v159, 1.0
	v_pk_fma_f32 v[0:1], v[10:11], v[106:107], v[0:1]
	v_cvt_scalef32_pk_f32_fp4 v[10:11], v159, 1.0 op_sel:[1,0,0]
	v_pk_fma_f32 v[0:1], v[12:13], v[108:109], v[0:1]
	v_cvt_scalef32_pk_f32_fp4 v[12:13], v159, 1.0 op_sel:[0,1,0]
	v_pk_fma_f32 v[0:1], v[14:15], v[110:111], v[0:1]
	v_cvt_scalef32_pk_f32_fp4 v[14:15], v159, 1.0 op_sel:[1,1,0]
	v_pk_fma_f32 v[0:1], v[16:17], v[112:113], v[0:1]
	v_cvt_scalef32_pk_f32_fp4 v[16:17], v156, 1.0
	v_pk_fma_f32 v[0:1], v[18:19], v[114:115], v[0:1]
	s_nop 0
	v_pk_fma_f32 v[0:1], v[20:21], v[116:117], v[0:1]
	s_nop 0
	v_pk_fma_f32 v[0:1], v[22:23], v[118:119], v[0:1]
	s_nop 0
	v_pk_fma_f32 v[0:1], v[24:25], v[120:121], v[0:1]
	s_nop 0
	v_pk_fma_f32 v[0:1], v[26:27], v[122:123], v[0:1]
	s_nop 0
	v_pk_fma_f32 v[0:1], v[28:29], v[124:125], v[0:1]
	s_nop 0
	v_pk_fma_f32 v[0:1], v[30:31], v[126:127], v[0:1]
	s_nop 0
	v_add_f32_e32 v0, v0, v1
	v_mov_b32_e32 v1, v177
	s_nop 0
	v_add_f32_dpp v0, v0, v0 row_shr:1 row_mask:0xf bank_mask:0xf bound_ctrl:1
	s_nop 1
	v_add_f32_dpp v0, v0, v0 row_shr:2 row_mask:0xf bank_mask:0xf bound_ctrl:1
	s_nop 1
	v_add_f32_dpp v0, v0, v0 row_shr:4 row_mask:0xf bank_mask:0xf bound_ctrl:1
	s_nop 1
	v_add_f32_dpp v0, v0, v0 row_shr:8 row_mask:0xf bank_mask:0xf bound_ctrl:1
	s_nop 1
	v_mov_b32_dpp v1, v0 row_bcast:15 row_mask:0xa bank_mask:0xf
	v_add_f32_e32 v0, v0, v1
	s_nop 0
	v_readlane_b32 s6, v0, 31
	v_readlane_b32 s57, v0, 63
	s_nop 0
	v_mov_b32_e32 v0, s6
	v_cndmask_b32_e32 v0, v166, v0, vcc
	v_cmp_eq_u32_e32 vcc, s53, v72
	v_mov_b32_e32 v1, s57
	s_nop 0
	v_cndmask_b32_e32 v0, v0, v1, vcc
	v_mul_f32_e32 v0, v194, v0
	v_mul_f32_e32 v1, 0x3d372713, v0
	v_mul_f32_e32 v1, v0, v1
	v_fma_f32 v1, v0, v1, v0
	v_mul_f32_e32 v1, 0x3f4c422a, v1
	v_add_f32_e32 v1, v1, v1
	v_mul_f32_e32 v1, 0x3fb8aa3b, v1
	v_exp_f32_e32 v1, v1
	v_mul_f32_e32 v0, 0.5, v0
	v_add_f32_e32 v1, 1.0, v1
	v_div_scale_f32 v2, s[62:63], v1, v1, 2.0
	v_rcp_f32_e32 v3, v2
	s_nop 0
	v_fma_f32 v4, -v2, v3, 1.0
	v_fmac_f32_e32 v3, v4, v3
	v_div_scale_f32 v4, vcc, 2.0, v1, 2.0
	v_mul_f32_e32 v5, v4, v3
	v_fma_f32 v6, -v2, v5, v4
	v_fmac_f32_e32 v5, v6, v3
	v_fma_f32 v2, -v2, v5, v4
	v_div_fmas_f32 v2, v2, v3, v5
	v_div_fixup_f32 v1, v2, v1, 2.0
	v_sub_f32_e32 v1, 1.0, v1
	v_add_f32_e32 v1, 1.0, v1
	v_mul_f32_e32 v0, v0, v1
	v_mul_f32_e32 v18, v193, v0
	v_cvt_scalef32_pk_f32_fp4 v[0:1], v158, 1.0
	v_readlane_b32 s6, v18, s51
	v_cvt_scalef32_pk_f32_fp4 v[2:3], v158, 1.0 op_sel:[1,0,0]
	v_cvt_scalef32_pk_f32_fp4 v[4:5], v158, 1.0 op_sel:[0,1,0]
	v_cvt_scalef32_pk_f32_fp4 v[6:7], v158, 1.0 op_sel:[1,1,0]
	v_pk_fma_f32 v[0:1], v[0:1], s[6:7], v[128:129] op_sel_hi:[1,0,1]
	v_pk_fma_f32 v[2:3], v[2:3], s[6:7], v[130:131] op_sel_hi:[1,0,1]
	v_pk_fma_f32 v[4:5], s[6:7], v[4:5], v[132:133] op_sel_hi:[0,1,1]
	v_pk_fma_f32 v[6:7], s[6:7], v[6:7], v[134:135] op_sel_hi:[0,1,1]
	v_pk_fma_f32 v[8:9], s[6:7], v[8:9], v[136:137] op_sel_hi:[0,1,1]
	v_pk_fma_f32 v[10:11], s[6:7], v[10:11], v[138:139] op_sel_hi:[0,1,1]
	v_pk_fma_f32 v[12:13], s[6:7], v[12:13], v[140:141] op_sel_hi:[0,1,1]
	v_pk_fma_f32 v[14:15], s[6:7], v[14:15], v[142:143] op_sel_hi:[0,1,1]
	v_readlane_b32 s6, v18, s50
	s_nop 1
	v_pk_fma_f32 v[0:1], v[16:17], s[6:7], v[0:1] op_sel_hi:[1,0,1]
	v_cvt_scalef32_pk_f32_fp4 v[16:17], v156, 1.0 op_sel:[1,0,0]
	v_pk_fma_f32 v[2:3], v[16:17], s[6:7], v[2:3] op_sel_hi:[1,0,1]
	v_cvt_scalef32_pk_f32_fp4 v[16:17], v156, 1.0 op_sel:[0,1,0]
	v_pk_fma_f32 v[4:5], s[6:7], v[16:17], v[4:5] op_sel_hi:[0,1,1]
	v_cvt_scalef32_pk_f32_fp4 v[16:17], v156, 1.0 op_sel:[1,1,0]
	v_pk_fma_f32 v[6:7], s[6:7], v[16:17], v[6:7] op_sel_hi:[0,1,1]
	v_cvt_scalef32_pk_f32_fp4 v[16:17], v157, 1.0
	v_pk_fma_f32 v[8:9], s[6:7], v[16:17], v[8:9] op_sel_hi:[0,1,1]
	v_cvt_scalef32_pk_f32_fp4 v[16:17], v157, 1.0 op_sel:[1,0,0]
	v_pk_fma_f32 v[10:11], s[6:7], v[16:17], v[10:11] op_sel_hi:[0,1,1]
	v_cvt_scalef32_pk_f32_fp4 v[16:17], v157, 1.0 op_sel:[0,1,0]
	v_pk_fma_f32 v[12:13], s[6:7], v[16:17], v[12:13] op_sel_hi:[0,1,1]
	v_cvt_scalef32_pk_f32_fp4 v[16:17], v157, 1.0 op_sel:[1,1,0]
	v_pk_fma_f32 v[14:15], s[6:7], v[16:17], v[14:15] op_sel_hi:[0,1,1]
	v_readlane_b32 s6, v18, s49
	v_cvt_scalef32_pk_f32_fp4 v[16:17], v154, 1.0
	s_nop 0
	v_pk_fma_f32 v[0:1], v[16:17], s[6:7], v[0:1] op_sel_hi:[1,0,1]
	v_cvt_scalef32_pk_f32_fp4 v[16:17], v154, 1.0 op_sel:[1,0,0]
	v_pk_fma_f32 v[2:3], v[16:17], s[6:7], v[2:3] op_sel_hi:[1,0,1]
	v_cvt_scalef32_pk_f32_fp4 v[16:17], v154, 1.0 op_sel:[0,1,0]
	v_pk_fma_f32 v[4:5], s[6:7], v[16:17], v[4:5] op_sel_hi:[0,1,1]
	v_cvt_scalef32_pk_f32_fp4 v[16:17], v154, 1.0 op_sel:[1,1,0]
	v_pk_fma_f32 v[6:7], s[6:7], v[16:17], v[6:7] op_sel_hi:[0,1,1]
	v_cvt_scalef32_pk_f32_fp4 v[16:17], v155, 1.0
	v_pk_fma_f32 v[8:9], s[6:7], v[16:17], v[8:9] op_sel_hi:[0,1,1]
	v_cvt_scalef32_pk_f32_fp4 v[16:17], v155, 1.0 op_sel:[1,0,0]
	v_pk_fma_f32 v[10:11], s[6:7], v[16:17], v[10:11] op_sel_hi:[0,1,1]
	v_cvt_scalef32_pk_f32_fp4 v[16:17], v155, 1.0 op_sel:[0,1,0]
	v_pk_fma_f32 v[12:13], s[6:7], v[16:17], v[12:13] op_sel_hi:[0,1,1]
	v_cvt_scalef32_pk_f32_fp4 v[16:17], v155, 1.0 op_sel:[1,1,0]
	v_pk_fma_f32 v[14:15], s[6:7], v[16:17], v[14:15] op_sel_hi:[0,1,1]
	v_readlane_b32 s6, v18, s47
	v_cvt_scalef32_pk_f32_fp4 v[16:17], v152, 1.0
	s_nop 0
; __device__ void peer_gather_phase(const Params& P, int l, bool do_store) {
;     ...
; #pragma unroll
;       for (int j = 0; j < 8; ++j) {
;         const float a = __builtin_bit_cast(float, __builtin_amdgcn_readlane(__builtin_bit_cast(int, avec), kb + j));
;         const f32x2 aa = f32x2{a, a};
;         y[0] += aa * __builtin_amdgcn_cvt_scalef32_pk_f32_fp4(v8[j].x, 1.0f, 0); y[1] += aa * __builtin_amdgcn_cvt_scalef32_pk_f32_fp4(v8[j].x, 1.0f, 1);
;         y[2] += aa * __builtin_amdgcn_cvt_scalef32_pk_f32_fp4(v8[j].x, 1.0f, 2); y[3] += aa * __builtin_amdgcn_cvt_scalef32_pk_f32_fp4(v8[j].x, 1.0f, 3);
;         y[4] += aa * __builtin_amdgcn_cvt_scalef32_pk_f32_fp4(v8[j].y, 1.0f, 0); y[5] += aa * __builtin_amdgcn_cvt_scalef32_pk_f32_fp4(v8[j].y, 1.0f, 1);
;         y[6] += aa * __builtin_amdgcn_cvt_scalef32_pk_f32_fp4(v8[j].y, 1.0f, 2); y[7] += aa * __builtin_amdgcn_cvt_scalef32_pk_f32_fp4(v8[j].y, 1.0f, 3);
;       }
;     };
;     load_batch(uA, vA, 0);
; #pragma unroll 1
;     for (int bt = 0; bt < 16; bt += 2) {
;       load_batch(uB, vB, bt + 1);
;       compute_batch(uA, vA, bt);
;       load_batch(uA, vA, (bt + 2 < 16) ? bt + 2 : 15);
;       compute_batch(uB, vB, bt + 1);
;     }
	v_pk_fma_f32 v[0:1], v[16:17], s[6:7], v[0:1] op_sel_hi:[1,0,1]
	v_cvt_scalef32_pk_f32_fp4 v[16:17], v152, 1.0 op_sel:[1,0,0]
	v_pk_fma_f32 v[2:3], v[16:17], s[6:7], v[2:3] op_sel_hi:[1,0,1]
	v_cvt_scalef32_pk_f32_fp4 v[16:17], v152, 1.0 op_sel:[0,1,0]
	v_pk_fma_f32 v[4:5], s[6:7], v[16:17], v[4:5] op_sel_hi:[0,1,1]
	v_cvt_scalef32_pk_f32_fp4 v[16:17], v152, 1.0 op_sel:[1,1,0]
	v_pk_fma_f32 v[6:7], s[6:7], v[16:17], v[6:7] op_sel_hi:[0,1,1]
	v_cvt_scalef32_pk_f32_fp4 v[16:17], v153, 1.0
	v_pk_fma_f32 v[8:9], s[6:7], v[16:17], v[8:9] op_sel_hi:[0,1,1]
	v_cvt_scalef32_pk_f32_fp4 v[16:17], v153, 1.0 op_sel:[1,0,0]
	v_pk_fma_f32 v[10:11], s[6:7], v[16:17], v[10:11] op_sel_hi:[0,1,1]
	v_cvt_scalef32_pk_f32_fp4 v[16:17], v153, 1.0 op_sel:[0,1,0]
	v_pk_fma_f32 v[12:13], s[6:7], v[16:17], v[12:13] op_sel_hi:[0,1,1]
	v_cvt_scalef32_pk_f32_fp4 v[16:17], v153, 1.0 op_sel:[1,1,0]
	v_pk_fma_f32 v[14:15], s[6:7], v[16:17], v[14:15] op_sel_hi:[0,1,1]
	v_readlane_b32 s6, v18, s37
	v_cvt_scalef32_pk_f32_fp4 v[16:17], v150, 1.0
	s_nop 0
	v_pk_fma_f32 v[0:1], v[16:17], s[6:7], v[0:1] op_sel_hi:[1,0,1]
	v_cvt_scalef32_pk_f32_fp4 v[16:17], v150, 1.0 op_sel:[1,0,0]
	v_pk_fma_f32 v[2:3], v[16:17], s[6:7], v[2:3] op_sel_hi:[1,0,1]
	v_cvt_scalef32_pk_f32_fp4 v[16:17], v150, 1.0 op_sel:[0,1,0]
	v_pk_fma_f32 v[4:5], s[6:7], v[16:17], v[4:5] op_sel_hi:[0,1,1]
	v_cvt_scalef32_pk_f32_fp4 v[16:17], v150, 1.0 op_sel:[1,1,0]
	v_pk_fma_f32 v[6:7], s[6:7], v[16:17], v[6:7] op_sel_hi:[0,1,1]
	v_cvt_scalef32_pk_f32_fp4 v[16:17], v151, 1.0
	v_pk_fma_f32 v[8:9], s[6:7], v[16:17], v[8:9] op_sel_hi:[0,1,1]
	v_cvt_scalef32_pk_f32_fp4 v[16:17], v151, 1.0 op_sel:[1,0,0]
	v_pk_fma_f32 v[10:11], s[6:7], v[16:17], v[10:11] op_sel_hi:[0,1,1]
	v_cvt_scalef32_pk_f32_fp4 v[16:17], v151, 1.0 op_sel:[0,1,0]
	v_pk_fma_f32 v[12:13], s[6:7], v[16:17], v[12:13] op_sel_hi:[0,1,1]
	v_cvt_scalef32_pk_f32_fp4 v[16:17], v151, 1.0 op_sel:[1,1,0]
	v_pk_fma_f32 v[14:15], s[6:7], v[16:17], v[14:15] op_sel_hi:[0,1,1]
	v_readlane_b32 s6, v18, s33
	v_cvt_scalef32_pk_f32_fp4 v[16:17], v148, 1.0
	s_nop 0
	v_pk_fma_f32 v[0:1], v[16:17], s[6:7], v[0:1] op_sel_hi:[1,0,1]
	v_cvt_scalef32_pk_f32_fp4 v[16:17], v148, 1.0 op_sel:[1,0,0]
	v_pk_fma_f32 v[2:3], v[16:17], s[6:7], v[2:3] op_sel_hi:[1,0,1]
	v_cvt_scalef32_pk_f32_fp4 v[16:17], v148, 1.0 op_sel:[0,1,0]
	v_pk_fma_f32 v[4:5], s[6:7], v[16:17], v[4:5] op_sel_hi:[0,1,1]
	v_cvt_scalef32_pk_f32_fp4 v[16:17], v148, 1.0 op_sel:[1,1,0]
	v_pk_fma_f32 v[6:7], s[6:7], v[16:17], v[6:7] op_sel_hi:[0,1,1]
	v_cvt_scalef32_pk_f32_fp4 v[16:17], v149, 1.0
	v_pk_fma_f32 v[8:9], s[6:7], v[16:17], v[8:9] op_sel_hi:[0,1,1]
	v_cvt_scalef32_pk_f32_fp4 v[16:17], v149, 1.0 op_sel:[1,0,0]
	v_pk_fma_f32 v[10:11], s[6:7], v[16:17], v[10:11] op_sel_hi:[0,1,1]
	v_cvt_scalef32_pk_f32_fp4 v[16:17], v149, 1.0 op_sel:[0,1,0]
	v_pk_fma_f32 v[12:13], s[6:7], v[16:17], v[12:13] op_sel_hi:[0,1,1]
	v_cvt_scalef32_pk_f32_fp4 v[16:17], v149, 1.0 op_sel:[1,1,0]
	v_pk_fma_f32 v[14:15], s[6:7], v[16:17], v[14:15] op_sel_hi:[0,1,1]
	v_readlane_b32 s6, v18, s7
	v_cvt_scalef32_pk_f32_fp4 v[16:17], v146, 1.0
	s_nop 0
	v_pk_fma_f32 v[0:1], v[16:17], s[6:7], v[0:1] op_sel_hi:[1,0,1]
	v_cvt_scalef32_pk_f32_fp4 v[16:17], v146, 1.0 op_sel:[1,0,0]
	v_pk_fma_f32 v[2:3], v[16:17], s[6:7], v[2:3] op_sel_hi:[1,0,1]
	v_cvt_scalef32_pk_f32_fp4 v[16:17], v146, 1.0 op_sel:[0,1,0]
	v_pk_fma_f32 v[4:5], s[6:7], v[16:17], v[4:5] op_sel_hi:[0,1,1]
	v_cvt_scalef32_pk_f32_fp4 v[16:17], v146, 1.0 op_sel:[1,1,0]
	v_pk_fma_f32 v[6:7], s[6:7], v[16:17], v[6:7] op_sel_hi:[0,1,1]
	v_cvt_scalef32_pk_f32_fp4 v[16:17], v147, 1.0
	v_pk_fma_f32 v[8:9], s[6:7], v[16:17], v[8:9] op_sel_hi:[0,1,1]
	v_cvt_scalef32_pk_f32_fp4 v[16:17], v147, 1.0 op_sel:[1,0,0]
	v_pk_fma_f32 v[10:11], s[6:7], v[16:17], v[10:11] op_sel_hi:[0,1,1]
	v_cvt_scalef32_pk_f32_fp4 v[16:17], v147, 1.0 op_sel:[0,1,0]
	v_pk_fma_f32 v[12:13], s[6:7], v[16:17], v[12:13] op_sel_hi:[0,1,1]
	v_cvt_scalef32_pk_f32_fp4 v[16:17], v147, 1.0 op_sel:[1,1,0]
	v_pk_fma_f32 v[14:15], s[6:7], v[16:17], v[14:15] op_sel_hi:[0,1,1]
	v_readlane_b32 s6, v18, s5
	v_cvt_scalef32_pk_f32_fp4 v[16:17], v144, 1.0
	s_nop 0
	v_pk_fma_f32 v[130:131], v[16:17], s[6:7], v[0:1] op_sel_hi:[1,0,1]
	v_cvt_scalef32_pk_f32_fp4 v[0:1], v144, 1.0 op_sel:[1,0,0]
	v_pk_fma_f32 v[138:139], v[0:1], s[6:7], v[2:3] op_sel_hi:[1,0,1]
	v_cvt_scalef32_pk_f32_fp4 v[0:1], v144, 1.0 op_sel:[0,1,0]
	v_pk_fma_f32 v[140:141], s[6:7], v[0:1], v[4:5] op_sel_hi:[0,1,1]
	v_cvt_scalef32_pk_f32_fp4 v[0:1], v144, 1.0 op_sel:[1,1,0]
	v_pk_fma_f32 v[142:143], s[6:7], v[0:1], v[6:7] op_sel_hi:[0,1,1]
	v_cvt_scalef32_pk_f32_fp4 v[0:1], v145, 1.0
	v_pk_fma_f32 v[128:129], s[6:7], v[0:1], v[8:9] op_sel_hi:[0,1,1]
	v_cvt_scalef32_pk_f32_fp4 v[0:1], v145, 1.0 op_sel:[1,0,0]
	v_pk_fma_f32 v[132:133], s[6:7], v[0:1], v[10:11] op_sel_hi:[0,1,1]
	v_cvt_scalef32_pk_f32_fp4 v[0:1], v145, 1.0 op_sel:[0,1,0]
	v_pk_fma_f32 v[134:135], s[6:7], v[0:1], v[12:13] op_sel_hi:[0,1,1]
	v_cvt_scalef32_pk_f32_fp4 v[0:1], v145, 1.0 op_sel:[1,1,0]
	v_pk_fma_f32 v[136:137], s[6:7], v[0:1], v[14:15] op_sel_hi:[0,1,1]
	s_mov_b32 s6, s1
	s_cbranch_scc0 .LBB0_22
; __device__ void peer_gather_phase(const Params& P, int l, bool do_store) {
;     ...
;     float* xfp = P.out + (size_t)t * 1024 + lane * 16;
;     float pre[16];
; #pragma unroll
;     for (int k2 = 0; k2 < 8; ++k2) {
;       pre[2 * k2 + 0] = ALPHA_C * xf[k2].x + y[k2].x;
;       pre[2 * k2 + 1] = ALPHA_C * xf[k2].y + y[k2].y;
;     }
;     float sm = 0.f;
; #pragma unroll
;     for (int k = 0; k < 16; ++k) sm += pre[k];
;     const float mean = wave_sum(sm) * (1.f / 1024.f);
;     float vs = 0.f;
; #pragma unroll
;     for (int k = 0; k < 16; ++k) { const float dd = pre[k] - mean; vs += dd * dd; }
;     const float rstd = rsqrtf(wave_sum(vs) * (1.f / 1024.f) + EPS_C);
;     const float* g2 = P.ln2_g + l * 1024 + lane * 16;
;     const float* b2 = P.ln2_b + l * 1024 + lane * 16;
;     float o[16];
; #pragma unroll
;     for (int k4 = 0; k4 < 4; ++k4) {
;       const float4 gg = *(const float4*)(g2 + 4 * k4), bb = *(const float4*)(b2 + 4 * k4);
;       o[4 * k4 + 0] = (pre[4 * k4 + 0] - mean) * rstd * gg.x + bb.x; o[4 * k4 + 1] = (pre[4 * k4 + 1] - mean) * rstd * gg.y + bb.y;
;       o[4 * k4 + 2] = (pre[4 * k4 + 2] - mean) * rstd * gg.z + bb.z; o[4 * k4 + 3] = (pre[4 * k4 + 3] - mean) * rstd * gg.w + bb.w;
;       float4 ov; ov.x = o[4 * k4]; ov.y = o[4 * k4 + 1]; ov.z = o[4 * k4 + 2]; ov.w = o[4 * k4 + 3];
;       if (do_store && l == 1) *(float4*)(xfp + 4 * k4) = ov;
;     }
	s_waitcnt vmcnt(0)
	v_lshlrev_b32_e32 v0, 16, v70
	v_lshlrev_b32_e32 v2, 16, v69
	v_and_b32_e32 v3, 0xffff0000, v69
	v_and_b32_e32 v1, 0xffff0000, v70
	s_mov_b32 s0, 0x3fb504f3
	v_pk_fma_f32 v[16:17], v[0:1], s[0:1], v[140:141] op_sel_hi:[1,0,1]
	v_pk_fma_f32 v[18:19], v[2:3], s[0:1], v[138:139] op_sel_hi:[1,0,1]
	global_load_dwordx4 v[0:3], v[82:83], off
	global_load_dwordx4 v[20:23], v[84:85], off
	v_lshlrev_b32_e32 v4, 16, v68
	v_and_b32_e32 v5, 0xffff0000, v68
	v_pk_fma_f32 v[4:5], v[4:5], s[0:1], v[130:131] op_sel_hi:[1,0,1]
	v_lshlrev_b32_e32 v10, 16, v71
	v_add_f32_e32 v24, 0, v4
	v_add_f32_e32 v24, v5, v24
	v_add_f32_e32 v24, v18, v24
	v_add_f32_e32 v24, v19, v24
	v_and_b32_e32 v11, 0xffff0000, v71
	v_add_f32_e32 v24, v16, v24
	v_pk_fma_f32 v[10:11], v[10:11], s[0:1], v[142:143] op_sel_hi:[1,0,1]
	v_add_f32_e32 v24, v17, v24
	v_lshlrev_b32_e32 v6, 16, v64
	v_lshlrev_b32_e32 v8, 16, v66
	v_lshlrev_b32_e32 v12, 16, v65
	v_lshlrev_b32_e32 v14, 16, v67
	v_and_b32_e32 v7, 0xffff0000, v64
	v_and_b32_e32 v13, 0xffff0000, v65
	v_and_b32_e32 v9, 0xffff0000, v66
	v_and_b32_e32 v15, 0xffff0000, v67
	v_add_f32_e32 v24, v10, v24
	v_add_f32_e32 v26, v11, v24
	v_pk_fma_f32 v[24:25], v[14:15], s[0:1], v[136:137] op_sel_hi:[1,0,1]
	v_pk_fma_f32 v[14:15], v[8:9], s[0:1], v[134:135] op_sel_hi:[1,0,1]
	v_pk_fma_f32 v[8:9], v[12:13], s[0:1], v[132:133] op_sel_hi:[1,0,1]
	v_pk_fma_f32 v[12:13], v[6:7], s[0:1], v[128:129] op_sel_hi:[1,0,1]
	v_mov_b32_e32 v7, v177
	v_add_f32_e32 v6, v12, v26
	v_add_f32_e32 v6, v13, v6
	v_add_f32_e32 v6, v8, v6
	v_add_f32_e32 v6, v9, v6
	v_add_f32_e32 v6, v14, v6
	v_add_f32_e32 v6, v15, v6
	v_add_f32_e32 v6, v24, v6
	v_add_f32_e32 v6, v25, v6
	s_nop 1
	v_add_f32_dpp v6, v6, v6 row_shr:1 row_mask:0xf bank_mask:0xf bound_ctrl:1
	s_nop 1
	v_add_f32_dpp v6, v6, v6 row_shr:2 row_mask:0xf bank_mask:0xf bound_ctrl:1
	s_nop 1
	v_add_f32_dpp v6, v6, v6 row_shr:4 row_mask:0xf bank_mask:0xf bound_ctrl:1
	s_nop 1
	v_add_f32_dpp v6, v6, v6 row_shr:8 row_mask:0xf bank_mask:0xf bound_ctrl:1
	s_nop 1
	v_mov_b32_dpp v7, v6 row_bcast:15 row_mask:0xa bank_mask:0xf
	v_add_f32_e32 v6, v6, v7
	v_mov_b32_e32 v7, v177
	s_nop 1
	v_mov_b32_dpp v7, v6 row_bcast:31 row_mask:0xc bank_mask:0xf
	v_add_f32_e32 v6, v6, v7
	s_nop 0
	v_readlane_b32 s0, v6, 63
	s_nop 1
	v_mul_f32_e32 v26, s0, v210
	v_pk_add_f32 v[28:29], v[4:5], v[26:27] op_sel_hi:[1,0] neg_lo:[0,1] neg_hi:[0,1]
	v_pk_add_f32 v[32:33], v[18:19], v[26:27] op_sel_hi:[1,0] neg_lo:[0,1] neg_hi:[0,1]
	v_pk_mul_f32 v[30:31], v[28:29], v[28:29]
	v_pk_mul_f32 v[18:19], v[32:33], v[32:33]
	v_pk_add_f32 v[4:5], v[16:17], v[26:27] op_sel_hi:[1,0] neg_lo:[0,1] neg_hi:[0,1]
	v_pk_add_f32 v[6:7], v[10:11], v[26:27] op_sel_hi:[1,0] neg_lo:[0,1] neg_hi:[0,1]
	v_pk_add_f32 v[10:11], v[12:13], v[26:27] op_sel_hi:[1,0] neg_lo:[0,1] neg_hi:[0,1]
	v_pk_add_f32 v[8:9], v[8:9], v[26:27] op_sel_hi:[1,0] neg_lo:[0,1] neg_hi:[0,1]
	v_pk_add_f32 v[14:15], v[14:15], v[26:27] op_sel_hi:[1,0] neg_lo:[0,1] neg_hi:[0,1]
	v_pk_add_f32 v[12:13], v[24:25], v[26:27] op_sel_hi:[1,0] neg_lo:[0,1] neg_hi:[0,1]
	v_add_f32_e32 v26, v30, v31
	v_add_f32_e32 v18, v18, v26
	v_pk_mul_f32 v[16:17], v[4:5], v[4:5]
	v_add_f32_e32 v18, v19, v18
	v_add_f32_e32 v16, v16, v18
	v_pk_mul_f32 v[34:35], v[6:7], v[6:7]
	v_add_f32_e32 v16, v17, v16
	v_add_f32_e32 v16, v34, v16
	v_pk_mul_f32 v[36:37], v[10:11], v[10:11]
	v_add_f32_e32 v16, v35, v16
	v_add_f32_e32 v16, v36, v16
	v_pk_mul_f32 v[38:39], v[8:9], v[8:9]
	v_add_f32_e32 v16, v37, v16
	v_add_f32_e32 v16, v38, v16
	v_pk_mul_f32 v[40:41], v[14:15], v[14:15]
	v_add_f32_e32 v16, v39, v16
	v_add_f32_e32 v16, v40, v16
	v_pk_mul_f32 v[24:25], v[12:13], v[12:13]
	v_add_f32_e32 v16, v41, v16
	v_add_f32_e32 v16, v24, v16
	v_add_f32_e32 v16, v25, v16
	v_mov_b32_e32 v17, v177
	s_nop 0
	v_add_f32_dpp v16, v16, v16 row_shr:1 row_mask:0xf bank_mask:0xf bound_ctrl:1
	s_nop 1
	v_add_f32_dpp v16, v16, v16 row_shr:2 row_mask:0xf bank_mask:0xf bound_ctrl:1
	s_nop 1
	v_add_f32_dpp v16, v16, v16 row_shr:4 row_mask:0xf bank_mask:0xf bound_ctrl:1
	s_nop 1
	v_add_f32_dpp v16, v16, v16 row_shr:8 row_mask:0xf bank_mask:0xf bound_ctrl:1
	s_nop 1
	v_mov_b32_dpp v17, v16 row_bcast:15 row_mask:0xa bank_mask:0xf
	v_add_f32_e32 v16, v16, v17
	v_mov_b32_e32 v17, v177
	s_nop 1
	v_mov_b32_dpp v17, v16 row_bcast:31 row_mask:0xc bank_mask:0xf
	v_add_f32_e32 v16, v16, v17
	s_nop 0
	v_readlane_b32 s0, v16, 63
	s_nop 1
	v_fma_f32 v16, s0, v210, v203
	s_mov_b32 s0, 0x800000
	v_mul_f32_e32 v17, 0x4b800000, v16
	v_cmp_gt_f32_e32 vcc, s0, v16
	s_nop 1
	v_cndmask_b32_e32 v16, v16, v17, vcc
	v_rsq_f32_e32 v18, v16
	v_lshl_add_u64 v[16:17], v[94:95], 2, v[80:81]
	v_mul_f32_e32 v19, 0x45800000, v18
	v_cndmask_b32_e32 v18, v18, v19, vcc
	v_pk_mul_f32 v[24:25], v[28:29], v[18:19] op_sel_hi:[1,0]
	s_and_b64 vcc, exec, s[38:39]
	s_waitcnt vmcnt(0)
	v_pk_fma_f32 v[0:1], v[0:1], v[24:25], v[20:21]
	v_pk_mul_f32 v[20:21], v[32:33], v[18:19] op_sel_hi:[1,0]
	s_nop 0
	v_pk_fma_f32 v[2:3], v[2:3], v[20:21], v[22:23]
	s_cbranch_vccz .LBB0_25
	global_store_dwordx4 v[16:17], v[0:3], off

; __device__ void phase_prologue(const Params& P) {
;     ...
;   {
;     const size_t n16 = (size_t)2 * 8 * 2 * 256 * 64 * 2 / 16;
;     uint4 z; z.x = z.y = z.z = z.w = 0u;
;     for (size_t i = gtid; i < n16; i += gsz) ((uint4*)P.KC)[i] = z;
;   }
.LBB0_351:
	s_or_b64 exec, exec, s[0:1]
	s_mov_b64 s[0:1], 0x10000
	v_cmp_gt_u64_e32 vcc, s[0:1], v[0:1]
	s_and_saveexec_b64 s[0:1], vcc
	s_cbranch_execz .LBB0_12
	v_readlane_b32 s4, v249, 13
	v_readlane_b32 s5, v249, 14
	s_lshl_b64 s[40:41], s[2:3], 12
	s_mov_b64 s[42:43], 0
	v_lshl_add_u64 v[2:3], v[2:3], 4, s[4:5]
	v_mov_b32_e32 v4, 0
	v_mov_b32_e32 v5, 0
	v_mov_b32_e32 v6, 0
	v_mov_b32_e32 v7, 0
.LBB0_353:
	v_lshl_add_u64 v[0:1], v[0:1], 0, s[38:39]
	s_mov_b64 s[4:5], 0xffff
	v_cmp_lt_u64_e32 vcc, s[4:5], v[0:1]
	global_store_dwordx4 v[2:3], v[4:7], off offset:-8
	s_or_b64 s[42:43], vcc, s[42:43]
	v_lshl_add_u64 v[2:3], v[2:3], 0, s[40:41]
	s_andn2_b64 exec, exec, s[42:43]
	s_cbranch_execnz .LBB0_353
	s_branch .LBB0_12
